# full stack with generic-grid guard on the P1 sample-tile reassignment
# baseline (speedup 1.0000x reference)
; __global__ void __launch_bounds__(NWAVES * 64, 2) hymba_fwd(Args args) {
;     ...
;             { int tid = threadIdx.x; asm volatile("" : "+v"(tid));
;               for (int t_ = bx; t_ < 256; t_ += G) { const int grow0 = MP + 32 * (t_ >> 4), gcol0 = 96 * (t_ & 15);
;                   SF_In f_{grow0, gcol0, SA, US, (OV_UG - OV_US) / 2}; small_gemm_tile<96, 8, 1, DM, 4>(lds, tid, HIN, DM, (const bf16*)(wl + WO_IN), grow0, gcol0, f_); } }
.LBB0_564:
	v_readlane_b32 s0, v253, 35
	v_readlane_b32 s1, v253, 36
	v_mov_b32_e32 v5, v0
	s_andn2_b64 vcc, exec, s[0:1]
	s_cbranch_vccnz .LBB0_576
	v_bfe_u32 v4, v5, 4, 2
	v_lshlrev_b32_e32 v2, 3, v4
	s_movk_i32 s0, 0x300
	v_and_b32_e32 v24, 15, v5
	v_lshl_add_u32 v4, v4, 4, 0
	v_cmp_gt_i32_e32 vcc, s0, v5
	v_lshlrev_b32_e32 v6, 1, v2
	s_mov_b32 s4, s56
	s_mov_b32 s5, s56
	s_cmpk_lg_i32 s51, 0x100
	s_cbranch_scc1 .LBB0_567
	s_cmpk_lt_i32 s56, 0x80
	s_cbranch_scc1 .LBB0_576
	s_add_i32 s4, s56, 0xffffff80
	s_add_i32 s5, s56, 0xffffff80
	s_branch .LBB0_567
.LBB0_566:
	s_or_b64 exec, exec, s[16:17]
	s_cmpk_lg_i32 s51, 0x100
	s_cselect_b32 s0, s51, 0x80
	s_add_i32 s5, s5, s0
	s_add_i32 s4, s4, s0
	s_cmpk_gt_i32 s5, 0xff
	s_barrier
	s_cbranch_scc1 .LBB0_576
